# v7 + GEMM prologue drain relaxed to vmcnt(6) (U, gates, W_out) + EpiUT row biases fetched up front
# speedup vs baseline: 1.0022x; 1.0022x over previous
.LBB0_432:
	v_readlane_b32 s8, v254, 2
	v_readlane_b32 s9, v254, 3
	v_mov_b32_e32 v13, v234
	s_andn2_b64 vcc, exec, s[8:9]
	v_cndmask_b32_e64 v0, 0, 1, s[8:9]
	v_cmp_ne_u32_e64 s[6:7], 1, v0
	v_readfirstlane_b32 s20, v13
	s_cbranch_vccnz .LBB0_448
	v_lshlrev_b32_e32 v0, 4, v13
	v_add_u32_e32 v1, 0x2000, v0
	v_ashrrev_i32_e32 v2, 31, v1
	v_lshrrev_b32_e32 v2, 22, v2
	v_add_u32_e32 v2, v1, v2
	v_ashrrev_i32_e32 v12, 10, v2
	v_mul_i32_i24_e32 v2, 0x400, v12
	v_sub_u32_e32 v1, v1, v2
	v_lshrrev_b32_e32 v2, 4, v1
	v_bitop3_b32 v1, v2, v1, 32 bitop3:0x6c
	v_ashrrev_i32_e32 v2, 31, v1
	v_lshrrev_b32_e32 v2, 26, v2
	v_add_u32_e32 v2, v1, v2
	v_lshlrev_b32_e32 v3, 3, v12
	v_ashrrev_i32_e32 v14, 6, v2
	v_and_b32_e32 v3, -16, v3
	s_mov_b64 s[8:9], 0x600000
	v_add_u32_e32 v3, v14, v3
	v_lshl_add_u64 v[128:129], v[160:161], 0, s[8:9]
	v_and_b32_e32 v4, 3, v14
	s_mov_b32 s8, 0x1fffe0
	v_lshrrev_b32_e32 v5, 2, v3
	v_lshlrev_b32_e32 v6, 1, v3
	v_and_b32_e32 v2, 0xc0, v2
	v_and_or_b32 v4, v3, s8, v4
	v_and_b32_e32 v5, 4, v5
	v_and_b32_e32 v6, 24, v6
	v_sub_u32_e32 v1, v1, v2
	v_mov_b32_e32 v2, 1
	v_or3_b32 v4, v4, v5, v6
	v_lshlrev_b32_e32 v5, 5, v12
	v_ashrrev_i16_sdwa v1, v2, sext(v1) dst_sel:DWORD dst_unused:UNUSED_PAD src0_sel:DWORD src1_sel:BYTE_0
	v_and_b32_e32 v5, 32, v5
	v_bfe_i32 v15, v1, 0, 16
	v_add_lshl_u32 v1, v5, v15, 1
	v_lshl_add_u32 v130, v4, 11, v1
	v_lshl_add_u32 v132, v3, 11, v1
	v_bfe_i32 v1, v13, 27, 1
	v_lshrrev_b32_e32 v1, 22, v1
	v_add_u32_e32 v1, v0, v1
	v_and_b32_e32 v1, 0xfffffc00, v1
	v_sub_u32_e32 v0, v0, v1
	v_lshrrev_b32_e32 v1, 4, v0
	v_ashrrev_i32_e32 v3, 31, v13
	v_bitop3_b32 v0, v1, v0, 32 bitop3:0x6c
	v_lshrrev_b32_e32 v3, 26, v3
	v_ashrrev_i32_e32 v1, 31, v0
	v_add_u32_e32 v3, v13, v3
	v_lshrrev_b32_e32 v1, 26, v1
	v_ashrrev_i32_e32 v17, 6, v3
	v_add_u32_e32 v1, v0, v1
	v_lshlrev_b32_e32 v3, 3, v17
	v_ashrrev_i32_e32 v16, 6, v1
	v_and_b32_e32 v3, -16, v3
	v_add_u32_e32 v3, v16, v3
	v_and_b32_e32 v4, 3, v16
	v_and_or_b32 v4, v3, s8, v4
	s_lshr_b32 s8, s95, 31
	s_ashr_i32 s9, s95, 8
	s_add_i32 s8, s9, s8
	s_mul_i32 s9, s8, 0xfffffb80
	s_add_i32 s9, s9, s2
	s_ashr_i32 s10, s9, 31
	s_lshr_b32 s10, s10, 29
	s_add_i32 s10, s9, s10
	s_ashr_i32 s21, s20, 6
	s_ashr_i32 s11, s10, 3
	s_and_b32 s10, s10, -8
	s_ashr_i32 s24, s20, 8
	s_lshl_b32 s22, s21, 10
	s_sub_i32 s9, s9, s10
	s_cmp_lt_i32 s9, 0
	s_movk_i32 s23, 0x91
	s_cselect_b32 s10, s23, 0x90
	s_mul_i32 s9, s10, s9
	s_add_i32 s9, s9, s11
	s_mul_hi_i32 s10, s9, 0x2aaaaaab
	s_lshr_b32 s11, s10, 31
	s_ashr_i32 s10, s10, 7
	s_add_i32 s10, s10, s11
	s_lshl_b32 s11, s10, 3
	v_and_b32_e32 v1, 0xc0, v1
	s_sub_i32 s12, 12, s11
	v_sub_u32_e32 v0, v0, v1
	s_min_i32 s12, s12, 8
	v_ashrrev_i16_sdwa v0, v2, sext(v0) dst_sel:DWORD dst_unused:UNUSED_PAD src0_sel:DWORD src1_sel:BYTE_0
	s_abs_i32 s13, s12
	s_waitcnt vmcnt(3)
	v_bfe_i32 v18, v0, 0, 16
	v_cvt_f32_u32_e32 v0, s13
	s_sub_i32 s15, 0, s13
	s_mulk_i32 s10, 0x300
	s_sub_i32 s9, s9, s10
	v_rcp_iflag_f32_e32 v0, v0
	s_abs_i32 s14, s9
	s_xor_b32 s10, s9, s12
	s_ashr_i32 s10, s10, 31
	v_mul_f32_e32 v0, 0x4f7ffffe, v0
	v_cvt_u32_f32_e32 v0, v0
	v_lshrrev_b32_e32 v5, 2, v3
	v_lshlrev_b32_e32 v6, 1, v3
	v_and_b32_e32 v5, 4, v5
	v_readfirstlane_b32 s16, v0
	s_mul_i32 s15, s15, s16
	s_mul_hi_u32 s15, s16, s15
	s_add_i32 s16, s16, s15
	s_mul_hi_u32 s15, s14, s16
	s_mul_i32 s16, s15, s13
	s_sub_i32 s14, s14, s16
	s_add_i32 s16, s15, 1
	s_sub_i32 s17, s14, s13
	s_cmp_ge_u32 s14, s13
	s_cselect_b32 s15, s16, s15
	s_cselect_b32 s14, s17, s14
	s_add_i32 s16, s15, 1
	s_cmp_ge_u32 s14, s13
	s_cselect_b32 s13, s16, s15
	s_xor_b32 s13, s13, s10
	s_sub_i32 s36, s13, s10
	s_mul_i32 s10, s36, s12
	v_and_b32_e32 v6, 24, v6
	s_sub_i32 s9, s9, s10
	v_or3_b32 v4, v4, v5, v6
	v_lshlrev_b32_e32 v5, 5, v17
	s_add_i32 s38, s9, s11
	v_and_b32_e32 v5, 32, v5
	s_ashr_i32 s39, s38, 31
	v_add_lshl_u32 v1, v5, v18, 1
	s_lshl_b64 s[10:11], s[38:39], 19
	s_ashr_i32 s37, s36, 31
	v_lshl_add_u32 v136, v3, 11, v1
	s_ashr_i32 s9, s8, 31
	v_lshl_add_u64 v[2:3], v[128:129], 0, s[10:11]
	s_lshl_b64 s[10:11], s[36:37], 19
	v_lshl_add_u32 v134, v4, 11, v1
	s_lshl_b64 s[8:9], s[8:9], 11
	v_lshl_add_u64 v[0:1], v[184:185], 0, s[10:11]
	v_lshl_add_u64 v[0:1], v[0:1], 0, s[8:9]
	s_add_i32 s33, s22, 0
	v_mov_b32_e32 v135, 0
	s_add_i32 m0, s33, 0x10000
	v_lshl_add_u64 v[4:5], v[0:1], 0, v[134:135]
	v_mov_b32_e32 v131, v135
	s_mov_b64 s[10:11], 0x40000
	global_load_lds_dwordx4 v[4:5], off
	v_lshl_add_u64 v[6:7], v[0:1], 0, v[130:131]
	s_add_i32 m0, s33, 0x12000
	v_lshl_add_u64 v[8:9], v[0:1], 0, s[10:11]
	global_load_lds_dwordx4 v[6:7], off
	s_add_i32 m0, s33, 0x14000
	v_lshl_add_u64 v[10:11], v[8:9], 0, v[134:135]
	global_load_lds_dwordx4 v[10:11], off
	v_lshl_add_u64 v[8:9], v[8:9], 0, v[130:131]
	s_add_i32 m0, s33, 0x16000
	v_lshl_add_u64 v[2:3], v[2:3], 0, s[8:9]
	v_mov_b32_e32 v137, v135
	global_load_lds_dwordx4 v[8:9], off
	v_lshl_add_u64 v[8:9], v[2:3], 0, v[136:137]
	s_mov_b32 m0, s33
	v_mov_b32_e32 v133, v135
	s_add_i32 s37, s33, 0x2000
	global_load_lds_dwordx4 v[8:9], off
	v_lshl_add_u64 v[10:11], v[2:3], 0, v[132:133]
	s_mov_b32 m0, s37
	v_lshl_add_u64 v[20:21], v[2:3], 0, s[10:11]
	s_add_i32 s39, s33, 0x4000
	global_load_lds_dwordx4 v[10:11], off
	s_waitcnt vmcnt(6)
	v_lshl_add_u64 v[22:23], v[20:21], 0, v[136:137]
	s_mov_b32 m0, s39
	s_add_i32 s42, s33, 0x6000
	global_load_lds_dwordx4 v[22:23], off
	v_lshl_add_u64 v[20:21], v[20:21], 0, v[132:133]
	s_mov_b32 m0, s42
	s_load_dwordx2 s[8:9], s[0:1], 0x58
	global_load_lds_dwordx4 v[20:21], off
	s_cmp_eq_u32 s24, 1
	s_cselect_b64 s[12:13], -1, 0
	s_cmp_lg_u32 s24, 1
	s_mov_b32 s43, 0
	s_cbranch_scc1 .LBB0_435
	s_barrier

.LBB0_690:
	v_ashrrev_i32_e32 v1, 31, v12
	v_lshrrev_b32_e32 v1, 26, v1
	v_add_u32_e32 v1, v12, v1
	v_ashrrev_i32_e32 v13, 6, v1
	v_bfe_i32 v1, v12, 27, 1
	v_lshlrev_b32_e32 v0, 4, v12
	v_lshrrev_b32_e32 v1, 22, v1
	v_add_u32_e32 v1, v0, v1
	v_and_b32_e32 v1, 0xfffffc00, v1
	v_sub_u32_e32 v1, v0, v1
	v_lshrrev_b32_e32 v2, 4, v1
	v_bitop3_b32 v1, v2, v1, 32 bitop3:0x6c
	v_ashrrev_i32_e32 v3, 31, v1
	v_lshrrev_b32_e32 v3, 26, v3
	v_add_u32_e32 v3, v1, v3
	v_lshlrev_b32_e32 v2, 3, v13
	v_ashrrev_i32_e32 v14, 6, v3
	v_and_b32_e32 v3, 0xc0, v3
	v_and_b32_e32 v2, -16, v2
	v_sub_u32_e32 v1, v1, v3
	v_mov_b32_e32 v3, 1
	s_mov_b64 s[6:7], 0xc00000
	v_add_u32_e32 v2, v14, v2
	v_ashrrev_i16_sdwa v1, v3, sext(v1) dst_sel:DWORD dst_unused:UNUSED_PAD src0_sel:DWORD src1_sel:BYTE_0
	v_lshl_add_u64 v[164:165], v[160:161], 0, s[6:7]
	v_lshlrev_b32_e32 v4, 5, v13
	v_bfe_i32 v15, v1, 0, 16
	v_lshlrev_b32_e32 v1, 1, v2
	v_lshrrev_b32_e32 v5, 2, v2
	v_and_b32_e32 v6, 3, v14
	s_mov_b32 s6, 0x1fffe0
	v_and_b32_e32 v4, 32, v4
	v_and_b32_e32 v1, 24, v1
	v_and_b32_e32 v5, 4, v5
	v_and_or_b32 v6, v2, s6, v6
	v_or3_b32 v1, v6, v5, v1
	v_add_lshl_u32 v4, v4, v15, 1
	v_add_u32_e32 v0, 0x2000, v0
	v_lshl_add_u32 v168, v1, 11, v4
	v_ashrrev_i32_e32 v1, 31, v0
	v_lshrrev_b32_e32 v1, 22, v1
	v_add_u32_e32 v1, v0, v1
	v_ashrrev_i32_e32 v16, 10, v1
	v_mul_i32_i24_e32 v1, 0x400, v16
	v_sub_u32_e32 v0, v0, v1
	v_lshrrev_b32_e32 v1, 4, v0
	v_bitop3_b32 v0, v1, v0, 32 bitop3:0x6c
	v_lshl_add_u32 v166, v2, 11, v4
	v_ashrrev_i32_e32 v2, 31, v0
	v_lshrrev_b32_e32 v2, 26, v2
	v_add_u32_e32 v2, v0, v2
	v_lshlrev_b32_e32 v1, 3, v16
	v_ashrrev_i32_e32 v17, 6, v2
	v_and_b32_e32 v2, 0xc0, v2
	v_and_b32_e32 v1, -16, v1
	v_sub_u32_e32 v0, v0, v2
	v_add_u32_e32 v1, v17, v1
	v_ashrrev_i16_sdwa v0, v3, sext(v0) dst_sel:DWORD dst_unused:UNUSED_PAD src0_sel:DWORD src1_sel:BYTE_0
	v_lshlrev_b32_e32 v4, 5, v16
	s_waitcnt vmcnt(3)
	v_bfe_i32 v18, v0, 0, 16
	v_lshlrev_b32_e32 v0, 1, v1
	v_lshrrev_b32_e32 v2, 2, v1
	v_and_b32_e32 v3, 3, v17
	v_and_b32_e32 v4, 32, v4
	v_and_b32_e32 v0, 24, v0
	v_and_b32_e32 v2, 4, v2
	v_and_or_b32 v3, v1, s6, v3
	s_waitcnt lgkmcnt(0)
	s_ashr_i32 s9, s8, 31
	v_or3_b32 v0, v3, v2, v0
	v_add_lshl_u32 v2, v4, v18, 1
	s_lshl_b64 s[10:11], s[8:9], 19
	s_ashr_i32 s35, s34, 31
	v_lshl_add_u32 v170, v1, 11, v2
	v_lshl_add_u32 v172, v0, 11, v2
	s_ashr_i32 s6, s20, 6
	v_lshl_add_u64 v[2:3], v[184:185], 0, s[10:11]
	s_lshl_b64 s[10:11], s[34:35], 19
	s_lshl_b32 s38, s6, 10
	v_lshl_add_u64 v[0:1], v[164:165], 0, s[10:11]
	v_lshl_add_u64 v[0:1], v[0:1], 0, s[12:13]
	s_add_i32 s39, s38, 0
	v_mov_b32_e32 v169, 0
	s_add_i32 m0, s39, 0x10000
	v_lshl_add_u64 v[4:5], v[0:1], 0, v[168:169]
	v_mov_b32_e32 v173, v169
	s_mov_b64 s[10:11], 0x40000
	global_load_lds_dwordx4 v[4:5], off
	v_lshl_add_u64 v[6:7], v[0:1], 0, v[172:173]
	s_add_i32 m0, s39, 0x12000
	v_lshl_add_u64 v[8:9], v[0:1], 0, s[10:11]
	global_load_lds_dwordx4 v[6:7], off
	s_add_i32 m0, s39, 0x14000
	v_lshl_add_u64 v[10:11], v[8:9], 0, v[168:169]
	global_load_lds_dwordx4 v[10:11], off
	v_lshl_add_u64 v[8:9], v[8:9], 0, v[172:173]
	s_add_i32 m0, s39, 0x16000
	v_lshl_add_u64 v[2:3], v[2:3], 0, s[12:13]
	v_mov_b32_e32 v167, v169
	global_load_lds_dwordx4 v[8:9], off
	v_lshl_add_u64 v[8:9], v[2:3], 0, v[166:167]
	s_mov_b32 m0, s39
	v_mov_b32_e32 v171, v169
	s_add_i32 s40, s39, 0x2000
	global_load_lds_dwordx4 v[8:9], off
	v_lshl_add_u64 v[10:11], v[2:3], 0, v[170:171]
	s_mov_b32 m0, s40
	v_lshl_add_u64 v[20:21], v[2:3], 0, s[10:11]
	s_add_i32 s41, s39, 0x4000
	global_load_lds_dwordx4 v[10:11], off
	s_waitcnt vmcnt(6)
	v_lshl_add_u64 v[22:23], v[20:21], 0, v[166:167]
	s_mov_b32 m0, s41
	s_add_i32 s42, s39, 0x6000
	global_load_lds_dwordx4 v[22:23], off
	v_lshl_add_u64 v[20:21], v[20:21], 0, v[170:171]
	s_mov_b32 m0, s42
	s_load_dwordx2 s[12:13], s[0:1], 0x58
	global_load_lds_dwordx4 v[20:21], off
	s_ashr_i32 s7, s20, 8
	s_cmp_eq_u32 s7, 1
	s_cselect_b64 s[14:15], -1, 0
	s_cmp_lg_u32 s7, 1
	s_mov_b32 s43, 0
	s_cbranch_scc1 .LBB0_692
	s_barrier

.LBB0_950:
	v_ashrrev_i32_e32 v1, 31, v12
	v_lshrrev_b32_e32 v1, 26, v1
	v_add_u32_e32 v1, v12, v1
	v_ashrrev_i32_e32 v13, 6, v1
	v_bfe_i32 v1, v12, 27, 1
	v_lshlrev_b32_e32 v0, 4, v12
	v_lshrrev_b32_e32 v1, 22, v1
	v_add_u32_e32 v1, v0, v1
	v_and_b32_e32 v1, 0xfffffc00, v1
	v_sub_u32_e32 v1, v0, v1
	v_lshrrev_b32_e32 v2, 4, v1
	v_bitop3_b32 v1, v2, v1, 32 bitop3:0x6c
	v_ashrrev_i32_e32 v3, 31, v1
	v_lshrrev_b32_e32 v3, 26, v3
	v_add_u32_e32 v3, v1, v3
	v_lshlrev_b32_e32 v2, 3, v13
	v_ashrrev_i32_e32 v14, 6, v3
	v_and_b32_e32 v3, 0xc0, v3
	v_and_b32_e32 v2, -16, v2
	v_sub_u32_e32 v1, v1, v3
	v_mov_b32_e32 v3, 1
	s_mov_b64 s[4:5], 0x1600000
	v_add_u32_e32 v2, v14, v2
	v_ashrrev_i16_sdwa v1, v3, sext(v1) dst_sel:DWORD dst_unused:UNUSED_PAD src0_sel:DWORD src1_sel:BYTE_0
	v_lshl_add_u64 v[188:189], v[160:161], 0, s[4:5]
	v_lshlrev_b32_e32 v4, 5, v13
	v_bfe_i32 v15, v1, 0, 16
	v_lshlrev_b32_e32 v1, 1, v2
	v_lshrrev_b32_e32 v5, 2, v2
	v_and_b32_e32 v6, 3, v14
	s_mov_b32 s5, 0x1fffe0
	v_and_b32_e32 v4, 32, v4
	v_and_b32_e32 v1, 24, v1
	v_and_b32_e32 v5, 4, v5
	v_and_or_b32 v6, v2, s5, v6
	v_or3_b32 v1, v6, v5, v1
	v_add_lshl_u32 v4, v4, v15, 1
	v_add_u32_e32 v0, 0x2000, v0
	v_lshl_add_u32 v192, v1, 11, v4
	v_ashrrev_i32_e32 v1, 31, v0
	v_lshrrev_b32_e32 v1, 22, v1
	v_add_u32_e32 v1, v0, v1
	v_ashrrev_i32_e32 v16, 10, v1
	v_mul_i32_i24_e32 v1, 0x400, v16
	v_sub_u32_e32 v0, v0, v1
	v_lshrrev_b32_e32 v1, 4, v0
	v_bitop3_b32 v0, v1, v0, 32 bitop3:0x6c
	v_lshl_add_u32 v190, v2, 11, v4
	v_ashrrev_i32_e32 v2, 31, v0
	v_lshrrev_b32_e32 v2, 26, v2
	v_add_u32_e32 v2, v0, v2
	v_lshlrev_b32_e32 v1, 3, v16
	v_ashrrev_i32_e32 v17, 6, v2
	v_and_b32_e32 v2, 0xc0, v2
	v_and_b32_e32 v1, -16, v1
	v_sub_u32_e32 v0, v0, v2
	v_add_u32_e32 v1, v17, v1
	v_ashrrev_i16_sdwa v0, v3, sext(v0) dst_sel:DWORD dst_unused:UNUSED_PAD src0_sel:DWORD src1_sel:BYTE_0
	v_lshlrev_b32_e32 v4, 5, v16
	s_waitcnt vmcnt(3)
	v_bfe_i32 v18, v0, 0, 16
	v_lshlrev_b32_e32 v0, 1, v1
	v_lshrrev_b32_e32 v2, 2, v1
	v_and_b32_e32 v3, 3, v17
	v_and_b32_e32 v4, 32, v4
	v_and_b32_e32 v0, 24, v0
	v_and_b32_e32 v2, 4, v2
	v_and_or_b32 v3, v1, s5, v3
	s_ashr_i32 s7, s6, 31
	v_or3_b32 v0, v3, v2, v0
	v_add_lshl_u32 v2, v4, v18, 1
	s_lshl_b64 s[12:13], s[6:7], 19
	s_ashr_i32 s67, s66, 31
	s_ashr_i32 s4, s10, 6
	v_lshl_add_u32 v194, v1, 11, v2
	v_lshl_add_u32 v196, v0, 11, v2
	v_lshl_add_u64 v[2:3], v[186:187], 0, s[12:13]
	s_lshl_b64 s[12:13], s[66:67], 19
	s_lshl_b32 s68, s4, 10
	v_lshl_add_u64 v[0:1], v[188:189], 0, s[12:13]
	v_mov_b32_e32 v199, 0
	v_lshl_add_u64 v[0:1], v[0:1], 0, s[8:9]
	s_add_i32 s69, s68, 0
	v_mov_b32_e32 v193, v199
	s_add_i32 m0, s69, 0x10000
	v_lshl_add_u64 v[4:5], v[0:1], 0, v[192:193]
	v_mov_b32_e32 v197, v199
	s_mov_b64 s[16:17], 0x40000
	global_load_lds_dwordx4 v[4:5], off
	v_lshl_add_u64 v[6:7], v[0:1], 0, v[196:197]
	s_add_i32 m0, s69, 0x12000
	v_lshl_add_u64 v[8:9], v[0:1], 0, s[16:17]
	global_load_lds_dwordx4 v[6:7], off
	s_add_i32 m0, s69, 0x14000
	v_lshl_add_u64 v[10:11], v[8:9], 0, v[192:193]
	global_load_lds_dwordx4 v[10:11], off
	v_lshl_add_u64 v[8:9], v[8:9], 0, v[196:197]
	s_add_i32 m0, s69, 0x16000
	v_lshl_add_u64 v[2:3], v[2:3], 0, s[8:9]
	v_mov_b32_e32 v191, v199
	global_load_lds_dwordx4 v[8:9], off
	v_lshl_add_u64 v[8:9], v[2:3], 0, v[190:191]
	s_mov_b32 m0, s69
	v_mov_b32_e32 v195, v199
	s_add_i32 s70, s69, 0x2000
	global_load_lds_dwordx4 v[8:9], off
	v_lshl_add_u64 v[10:11], v[2:3], 0, v[194:195]
	s_mov_b32 m0, s70
	v_lshl_add_u64 v[20:21], v[2:3], 0, s[16:17]
	s_add_i32 s71, s69, 0x4000
	global_load_lds_dwordx4 v[10:11], off
	s_waitcnt vmcnt(6)
	v_lshl_add_u64 v[22:23], v[20:21], 0, v[190:191]
	s_mov_b32 m0, s71
	s_add_i32 s72, s69, 0x6000
	global_load_lds_dwordx4 v[22:23], off
	v_lshl_add_u64 v[20:21], v[20:21], 0, v[194:195]
	s_mov_b32 m0, s72
	s_ashr_i32 s5, s10, 8
	global_load_lds_dwordx4 v[20:21], off
	s_load_dwordx4 s[12:15], s[0:1], 0x0
	s_load_dwordx2 s[18:19], s[0:1], 0xd0
	s_load_dwordx2 s[20:21], s[0:1], 0x100
	s_cmp_eq_u32 s5, 1
	s_cselect_b64 s[22:23], -1, 0
	s_cmp_lg_u32 s5, 1
	s_mov_b32 s25, 0
	s_cbranch_scc1 .LBB0_952
	s_barrier
